# LDS bank-conflict / wide-write strategy: attention V^T staging writes paired through DPP row_ror:8 into 4 dword writes per chunk instead of 8 two-byte scatter writes
# speedup vs baseline: 1.0060x; 1.0060x over previous
; #define LAS __attribute__((address_space(3)))
; __device__ __forceinline__ void attn_unit(LAS unsigned char* lds, const bf16* PROJ, bf16* DA, const float* sinkl, int unit, int tid, int wid, int lane) {
;     ...
;     const int s0 = (n - 1) * 128;
; #pragma unroll
;     for (int hp = 0; hp < 2; ++hp) {
;         v4u kreg[3], vreg[3];
; #pragma unroll
;         for (int i = 0; i < 3; ++i) {
;             const int idx = tid + 512 * (3 * hp + i), c = idx >> 3, ch = idx & 7, s = s0 + c;
;             if (s >= 0 && s < SEQ) { const bf16* p = PROJ + (rowb + s) * INW + 1024 + hk * 64 + ch * 8; kreg[i] = *(const v4u*)p; vreg[i] = *(const v4u*)(p + 128); }
;             else { kreg[i] = (v4u){0u, 0u, 0u, 0u}; vreg[i] = (v4u){0u, 0u, 0u, 0u}; }
;         }
; #pragma unroll
;         for (int i = 0; i < 3; ++i) {
;             const int idx = tid + 512 * (3 * hp + i), c = idx >> 3, ch = idx & 7;
;             *(LAS v4u*)(Ks + c * KS_PITCH + ch * 8) = kreg[i];
;             LAS bf16* vp = Vt + (ch * 8) * VT_PITCH + c;
;             vp[0 * VT_PITCH] = (bf16)(vreg[i].x & 0xffffu); vp[1 * VT_PITCH] = (bf16)(vreg[i].x >> 16);
;             vp[2 * VT_PITCH] = (bf16)(vreg[i].y & 0xffffu); vp[3 * VT_PITCH] = (bf16)(vreg[i].y >> 16);
;             vp[4 * VT_PITCH] = (bf16)(vreg[i].z & 0xffffu); vp[5 * VT_PITCH] = (bf16)(vreg[i].z >> 16);
;             vp[6 * VT_PITCH] = (bf16)(vreg[i].w & 0xffffu); vp[7 * VT_PITCH] = (bf16)(vreg[i].w >> 16);
;         }
.LBB0_355:
	s_and_b64 vcc, exec, s[36:37]
	s_cbranch_vccz .LBB0_423
	v_lshlrev_b32_e32 v2, 3, v173
	v_ashrrev_i32_e32 v42, 3, v173
	v_readlane_b32 s13, v239, 10
	v_and_b32_e32 v41, 56, v2
	v_lshlrev_b32_e32 v38, 1, v41
	v_mov_b32_e32 v39, v66
	s_waitcnt lgkmcnt(0)
	v_readlane_b32 s6, v239, 6
	v_readlane_b32 s7, v239, 7
	v_readlane_b32 s12, v239, 9
	s_lshl_b64 s[24:25], s[70:71], 2
	v_readlane_b32 s32, v239, 11
	s_add_u32 s24, s32, s24
	v_readlane_b32 s32, v239, 12
	s_addc_u32 s25, s32, s25
	v_readlane_b32 s88, v238, 7
	v_readlane_b32 s89, v238, 8
	v_bfe_u32 v189, v173, 5, 1
	v_lshlrev_b32_e32 v192, 4, v189
	v_mov_b32_e32 v193, v66
	v_lshl_add_u64 v[192:193], s[88:89], 0, v[192:193]
	v_and_b32_e32 v189, 31, v173
	v_or_b32_e32 v189, s80, v189
	v_or_b32_e32 v189, s12, v189
	v_or_b32_e32 v189, s6, v189
	v_mad_u64_u32 v[192:193], s[88:89], v189, s82, v[192:193]
	v_mad_i32_i24 v193, s7, v201, v193
	global_load_dwordx4 v[68:71], v[192:193], off offset:1024
	global_load_dwordx4 v[72:75], v[192:193], off offset:1056
	global_load_dwordx4 v[76:79], v[192:193], off offset:1088
	global_load_dwordx4 v[80:83], v[192:193], off offset:1120
	global_load_dword v191, v66, s[24:25]
	v_readlane_b32 s72, v238, 5
	v_readlane_b32 s73, v238, 6
	s_movk_i32 s84, 0x1000
	v_add_u32_e32 v2, 0x200, v173
	v_ashrrev_i32_e32 v43, 3, v2
	v_add_u32_e32 v2, 0x400, v173
	v_ashrrev_i32_e32 v44, 3, v2
	v_add_u32_e32 v2, 0x600, v173
	v_ashrrev_i32_e32 v186, 3, v2
	v_add_u32_e32 v2, 0x800, v173
	v_ashrrev_i32_e32 v187, 3, v2
	v_add_u32_e32 v2, 0xa00, v173
	v_ashrrev_i32_e32 v188, 3, v2
	v_add_u32_e32 v189, s13, v42
	v_cmp_gt_u32_e64 s[28:29], s84, v189
	v_and_b32_e32 v189, 0xfff, v189
	v_or_b32_e32 v190, s6, v189
	v_mov_b64_e32 v[192:193], s[72:73]
	v_mad_u64_u32 v[192:193], s[88:89], v190, s82, v[192:193]
	v_mad_i32_i24 v193, s7, v201, v193
	v_lshl_add_u64 v[192:193], v[192:193], 0, v[38:39]
	global_load_dwordx4 v[26:29], v[192:193], off offset:2048
	global_load_dwordx4 v[174:177], v[192:193], off offset:2304
	v_add_u32_e32 v189, s13, v43
	v_cmp_gt_u32_e64 s[30:31], s84, v189
	v_and_b32_e32 v189, 0xfff, v189
	v_or_b32_e32 v190, s6, v189
	v_mov_b64_e32 v[192:193], s[72:73]
	v_mad_u64_u32 v[192:193], s[88:89], v190, s82, v[192:193]
	v_mad_i32_i24 v193, s7, v201, v193
	v_lshl_add_u64 v[192:193], v[192:193], 0, v[38:39]
	global_load_dwordx4 v[30:33], v[192:193], off offset:2048
	global_load_dwordx4 v[178:181], v[192:193], off offset:2304
	v_add_u32_e32 v189, s13, v44
	v_cmp_gt_u32_e64 s[34:35], s84, v189
	v_and_b32_e32 v189, 0xfff, v189
	v_or_b32_e32 v190, s6, v189
	v_mov_b64_e32 v[192:193], s[72:73]
	v_mad_u64_u32 v[192:193], s[88:89], v190, s82, v[192:193]
	v_mad_i32_i24 v193, s7, v201, v193
	v_lshl_add_u64 v[192:193], v[192:193], 0, v[38:39]
	global_load_dwordx4 v[34:37], v[192:193], off offset:2048
	global_load_dwordx4 v[182:185], v[192:193], off offset:2304
	v_add_u32_e32 v189, s13, v186
	v_cmp_gt_u32_e64 s[62:63], s84, v189
	v_and_b32_e32 v189, 0xfff, v189
	v_or_b32_e32 v190, s6, v189
	v_mov_b64_e32 v[192:193], s[72:73]
	v_mad_u64_u32 v[192:193], s[88:89], v190, s82, v[192:193]
	v_mad_i32_i24 v193, s7, v201, v193
	v_lshl_add_u64 v[192:193], v[192:193], 0, v[38:39]
	global_load_dwordx4 v[6:9], v[192:193], off offset:2048
	global_load_dwordx4 v[2:5], v[192:193], off offset:2304
	v_add_u32_e32 v189, s13, v187
	v_cmp_gt_u32_e64 s[74:75], s84, v189
	v_and_b32_e32 v189, 0xfff, v189
	v_or_b32_e32 v190, s6, v189
	v_mov_b64_e32 v[192:193], s[72:73]
	v_mad_u64_u32 v[192:193], s[88:89], v190, s82, v[192:193]
	v_mad_i32_i24 v193, s7, v201, v193
	v_lshl_add_u64 v[192:193], v[192:193], 0, v[38:39]
	global_load_dwordx4 v[14:17], v[192:193], off offset:2048
	global_load_dwordx4 v[10:13], v[192:193], off offset:2304
	v_add_u32_e32 v189, s13, v188
	v_cmp_gt_u32_e64 s[76:77], s84, v189
	v_and_b32_e32 v189, 0xfff, v189
	v_or_b32_e32 v190, s6, v189
	v_mov_b64_e32 v[192:193], s[72:73]
	v_mad_u64_u32 v[192:193], s[88:89], v190, s82, v[192:193]
	v_mad_i32_i24 v193, s7, v201, v193
	v_lshl_add_u64 v[192:193], v[192:193], 0, v[38:39]
	global_load_dwordx4 v[22:25], v[192:193], off offset:2048
	global_load_dwordx4 v[18:21], v[192:193], off offset:2304
	v_lshl_add_u32 v40, v41, 1, 0
	s_movk_i32 s32, 0x306
	v_mad_u32_u24 v41, v41, s32, v40
	v_and_b32_e32 v123, 8, v173
	v_cmp_eq_u32_e64 s[98:99], 0, v123
	v_mov_b32_e32 v136, 0x01000504
	v_mov_b32_e32 v137, 0x03020706
	v_mov_b32_e32 v138, 0x05040100
	v_cndmask_b32_e64 v136, v136, v138, s[98:99]
	v_mov_b32_e32 v138, 0x07060302
	v_cndmask_b32_e64 v137, v137, v138, s[98:99]
	v_mov_b32_e32 v138, 0xc20
	v_cndmask_b32_e64 v138, v138, 0, s[98:99]
	v_add_u32_e32 v138, v41, v138
	s_waitcnt vmcnt(11)
	v_cndmask_b32_e64 v26, 0, v26, s[28:29]
	v_cndmask_b32_e64 v27, 0, v27, s[28:29]
	v_cndmask_b32_e64 v28, 0, v28, s[28:29]
	v_cndmask_b32_e64 v29, 0, v29, s[28:29]
	v_mad_u32_u24 v121, v42, s3, v40
	ds_write_b128 v121, v[26:29]
	s_waitcnt vmcnt(10)
	v_cndmask_b32_e64 v174, 0, v174, s[28:29]
	v_cndmask_b32_e64 v175, 0, v175, s[28:29]
	v_cndmask_b32_e64 v176, 0, v176, s[28:29]
	v_cndmask_b32_e64 v177, 0, v177, s[28:29]
	v_and_b32_e32 v123, -2, v42
	v_lshl_add_u32 v122, v123, 1, v138
	s_nop 0
	v_mov_b32_dpp v124, v174 row_ror:8 row_mask:0xf bank_mask:0xf
	v_mov_b32_dpp v125, v175 row_ror:8 row_mask:0xf bank_mask:0xf
	v_mov_b32_dpp v126, v176 row_ror:8 row_mask:0xf bank_mask:0xf
	v_mov_b32_dpp v127, v177 row_ror:8 row_mask:0xf bank_mask:0xf
	v_cndmask_b32_e64 v128, v176, v174, s[98:99]
	v_cndmask_b32_e64 v129, v177, v175, s[98:99]
	v_cndmask_b32_e64 v130, v126, v124, s[98:99]
	v_cndmask_b32_e64 v131, v127, v125, s[98:99]
	v_perm_b32 v132, v130, v128, v136
	v_perm_b32 v133, v130, v128, v137
	v_perm_b32 v134, v131, v129, v136
	v_perm_b32 v135, v131, v129, v137
	ds_write_b32 v122, v132 offset:55296
	ds_write_b32 v122, v133 offset:56072
	ds_write_b32 v122, v134 offset:56848
	ds_write_b32 v122, v135 offset:57624
	s_waitcnt vmcnt(9)
; #define LAS __attribute__((address_space(3)))
; __device__ __forceinline__ void attn_unit(LAS unsigned char* lds, const bf16* PROJ, bf16* DA, const float* sinkl, int unit, int tid, int wid, int lane) {
;     ...
; #pragma unroll
;         for (int i = 0; i < 3; ++i) {
;             const int idx = tid + 512 * (3 * hp + i), c = idx >> 3, ch = idx & 7;
;             *(LAS v4u*)(Ks + c * KS_PITCH + ch * 8) = kreg[i];
;             LAS bf16* vp = Vt + (ch * 8) * VT_PITCH + c;
;             vp[0 * VT_PITCH] = (bf16)(vreg[i].x & 0xffffu); vp[1 * VT_PITCH] = (bf16)(vreg[i].x >> 16);
;             vp[2 * VT_PITCH] = (bf16)(vreg[i].y & 0xffffu); vp[3 * VT_PITCH] = (bf16)(vreg[i].y >> 16);
;             vp[4 * VT_PITCH] = (bf16)(vreg[i].z & 0xffffu); vp[5 * VT_PITCH] = (bf16)(vreg[i].z >> 16);
;             vp[6 * VT_PITCH] = (bf16)(vreg[i].w & 0xffffu); vp[7 * VT_PITCH] = (bf16)(vreg[i].w >> 16);
;         }
;     }
;     __syncthreads();
	v_cndmask_b32_e64 v30, 0, v30, s[30:31]
	v_cndmask_b32_e64 v31, 0, v31, s[30:31]
	v_cndmask_b32_e64 v32, 0, v32, s[30:31]
	v_cndmask_b32_e64 v33, 0, v33, s[30:31]
	v_mad_u32_u24 v121, v43, s3, v40
	ds_write_b128 v121, v[30:33]
	s_waitcnt vmcnt(8)
	v_cndmask_b32_e64 v178, 0, v178, s[30:31]
	v_cndmask_b32_e64 v179, 0, v179, s[30:31]
	v_cndmask_b32_e64 v180, 0, v180, s[30:31]
	v_cndmask_b32_e64 v181, 0, v181, s[30:31]
	v_and_b32_e32 v123, -2, v43
	v_lshl_add_u32 v122, v123, 1, v138
	s_nop 0
	v_mov_b32_dpp v124, v178 row_ror:8 row_mask:0xf bank_mask:0xf
	v_mov_b32_dpp v125, v179 row_ror:8 row_mask:0xf bank_mask:0xf
	v_mov_b32_dpp v126, v180 row_ror:8 row_mask:0xf bank_mask:0xf
	v_mov_b32_dpp v127, v181 row_ror:8 row_mask:0xf bank_mask:0xf
	v_cndmask_b32_e64 v128, v180, v178, s[98:99]
	v_cndmask_b32_e64 v129, v181, v179, s[98:99]
	v_cndmask_b32_e64 v130, v126, v124, s[98:99]
	v_cndmask_b32_e64 v131, v127, v125, s[98:99]
	v_perm_b32 v132, v130, v128, v136
	v_perm_b32 v133, v130, v128, v137
	v_perm_b32 v134, v131, v129, v136
	v_perm_b32 v135, v131, v129, v137
	ds_write_b32 v122, v132 offset:55296
	ds_write_b32 v122, v133 offset:56072
	ds_write_b32 v122, v134 offset:56848
	ds_write_b32 v122, v135 offset:57624
	s_waitcnt vmcnt(7)
	v_cndmask_b32_e64 v34, 0, v34, s[34:35]
	v_cndmask_b32_e64 v35, 0, v35, s[34:35]
	v_cndmask_b32_e64 v36, 0, v36, s[34:35]
	v_cndmask_b32_e64 v37, 0, v37, s[34:35]
	v_mad_u32_u24 v121, v44, s3, v40
	ds_write_b128 v121, v[34:37]
	s_waitcnt vmcnt(6)
	v_cndmask_b32_e64 v182, 0, v182, s[34:35]
	v_cndmask_b32_e64 v183, 0, v183, s[34:35]
	v_cndmask_b32_e64 v184, 0, v184, s[34:35]
	v_cndmask_b32_e64 v185, 0, v185, s[34:35]
	v_and_b32_e32 v123, -2, v44
	v_lshl_add_u32 v122, v123, 1, v138
	s_nop 0
	v_mov_b32_dpp v124, v182 row_ror:8 row_mask:0xf bank_mask:0xf
	v_mov_b32_dpp v125, v183 row_ror:8 row_mask:0xf bank_mask:0xf
	v_mov_b32_dpp v126, v184 row_ror:8 row_mask:0xf bank_mask:0xf
	v_mov_b32_dpp v127, v185 row_ror:8 row_mask:0xf bank_mask:0xf
	v_cndmask_b32_e64 v128, v184, v182, s[98:99]
	v_cndmask_b32_e64 v129, v185, v183, s[98:99]
	v_cndmask_b32_e64 v130, v126, v124, s[98:99]
	v_cndmask_b32_e64 v131, v127, v125, s[98:99]
	v_perm_b32 v132, v130, v128, v136
	v_perm_b32 v133, v130, v128, v137
	v_perm_b32 v134, v131, v129, v136
	v_perm_b32 v135, v131, v129, v137
	ds_write_b32 v122, v132 offset:55296
	ds_write_b32 v122, v133 offset:56072
	ds_write_b32 v122, v134 offset:56848
	ds_write_b32 v122, v135 offset:57624
	s_waitcnt vmcnt(5)
	v_cndmask_b32_e64 v6, 0, v6, s[62:63]
	v_cndmask_b32_e64 v7, 0, v7, s[62:63]
	v_cndmask_b32_e64 v8, 0, v8, s[62:63]
	v_cndmask_b32_e64 v9, 0, v9, s[62:63]
	v_mad_u32_u24 v121, v186, s3, v40
	ds_write_b128 v121, v[6:9]
	s_waitcnt vmcnt(4)
	v_cndmask_b32_e64 v2, 0, v2, s[62:63]
	v_cndmask_b32_e64 v3, 0, v3, s[62:63]
	v_cndmask_b32_e64 v4, 0, v4, s[62:63]
	v_cndmask_b32_e64 v5, 0, v5, s[62:63]
	v_and_b32_e32 v123, -2, v186
	v_lshl_add_u32 v122, v123, 1, v138
	s_nop 0
	v_mov_b32_dpp v124, v2 row_ror:8 row_mask:0xf bank_mask:0xf
	v_mov_b32_dpp v125, v3 row_ror:8 row_mask:0xf bank_mask:0xf
	v_mov_b32_dpp v126, v4 row_ror:8 row_mask:0xf bank_mask:0xf
	v_mov_b32_dpp v127, v5 row_ror:8 row_mask:0xf bank_mask:0xf
	v_cndmask_b32_e64 v128, v4, v2, s[98:99]
	v_cndmask_b32_e64 v129, v5, v3, s[98:99]
	v_cndmask_b32_e64 v130, v126, v124, s[98:99]
	v_cndmask_b32_e64 v131, v127, v125, s[98:99]
	v_perm_b32 v132, v130, v128, v136
	v_perm_b32 v133, v130, v128, v137
	v_perm_b32 v134, v131, v129, v136
	v_perm_b32 v135, v131, v129, v137
	ds_write_b32 v122, v132 offset:55296
	ds_write_b32 v122, v133 offset:56072
	ds_write_b32 v122, v134 offset:56848
	ds_write_b32 v122, v135 offset:57624
	s_waitcnt vmcnt(3)
	v_cndmask_b32_e64 v14, 0, v14, s[74:75]
	v_cndmask_b32_e64 v15, 0, v15, s[74:75]
	v_cndmask_b32_e64 v16, 0, v16, s[74:75]
	v_cndmask_b32_e64 v17, 0, v17, s[74:75]
	v_mad_u32_u24 v121, v187, s3, v40
	ds_write_b128 v121, v[14:17]
	s_waitcnt vmcnt(2)
	v_cndmask_b32_e64 v10, 0, v10, s[74:75]
	v_cndmask_b32_e64 v11, 0, v11, s[74:75]
	v_cndmask_b32_e64 v12, 0, v12, s[74:75]
	v_cndmask_b32_e64 v13, 0, v13, s[74:75]
	v_and_b32_e32 v123, -2, v187
	v_lshl_add_u32 v122, v123, 1, v138
	s_nop 0
	v_mov_b32_dpp v124, v10 row_ror:8 row_mask:0xf bank_mask:0xf
	v_mov_b32_dpp v125, v11 row_ror:8 row_mask:0xf bank_mask:0xf
	v_mov_b32_dpp v126, v12 row_ror:8 row_mask:0xf bank_mask:0xf
	v_mov_b32_dpp v127, v13 row_ror:8 row_mask:0xf bank_mask:0xf
	v_cndmask_b32_e64 v128, v12, v10, s[98:99]
	v_cndmask_b32_e64 v129, v13, v11, s[98:99]
	v_cndmask_b32_e64 v130, v126, v124, s[98:99]
	v_cndmask_b32_e64 v131, v127, v125, s[98:99]
	v_perm_b32 v132, v130, v128, v136
	v_perm_b32 v133, v130, v128, v137
	v_perm_b32 v134, v131, v129, v136
	v_perm_b32 v135, v131, v129, v137
	ds_write_b32 v122, v132 offset:55296
	ds_write_b32 v122, v133 offset:56072
	ds_write_b32 v122, v134 offset:56848
	ds_write_b32 v122, v135 offset:57624
	s_waitcnt vmcnt(1)
	v_cndmask_b32_e64 v22, 0, v22, s[76:77]
	v_cndmask_b32_e64 v23, 0, v23, s[76:77]
	v_cndmask_b32_e64 v24, 0, v24, s[76:77]
	v_cndmask_b32_e64 v25, 0, v25, s[76:77]
	v_mad_u32_u24 v121, v188, s3, v40
	ds_write_b128 v121, v[22:25]
	s_waitcnt vmcnt(0)
	v_cndmask_b32_e64 v18, 0, v18, s[76:77]
	v_cndmask_b32_e64 v19, 0, v19, s[76:77]
	v_cndmask_b32_e64 v20, 0, v20, s[76:77]
	v_cndmask_b32_e64 v21, 0, v21, s[76:77]
	v_and_b32_e32 v123, -2, v188
	v_lshl_add_u32 v122, v123, 1, v138
	s_nop 0
	v_mov_b32_dpp v124, v18 row_ror:8 row_mask:0xf bank_mask:0xf
	v_mov_b32_dpp v125, v19 row_ror:8 row_mask:0xf bank_mask:0xf
	v_mov_b32_dpp v126, v20 row_ror:8 row_mask:0xf bank_mask:0xf
	v_mov_b32_dpp v127, v21 row_ror:8 row_mask:0xf bank_mask:0xf
	v_cndmask_b32_e64 v128, v20, v18, s[98:99]
	v_cndmask_b32_e64 v129, v21, v19, s[98:99]
	v_cndmask_b32_e64 v130, v126, v124, s[98:99]
	v_cndmask_b32_e64 v131, v127, v125, s[98:99]
	v_perm_b32 v132, v130, v128, v136
	v_perm_b32 v133, v130, v128, v137
	v_perm_b32 v134, v131, v129, v136
	v_perm_b32 v135, v131, v129, v137
	ds_write_b32 v122, v132 offset:55296
	ds_write_b32 v122, v133 offset:56072
	ds_write_b32 v122, v134 offset:56848
	ds_write_b32 v122, v135 offset:57624
	s_waitcnt lgkmcnt(0)
	s_barrier
; #define ATT_QK(dst, cblk) do { _Pragma("unroll") for (int r = 0; r < 16; ++r) dst[r] = 0.f; \
;             _Pragma("unroll") for (int ks = 0; ks < 4; ++ks) { const bf16x8 kf = *(const LAS bf16x8*)(Ks + ((cblk) + r32) * KS_PITCH + ks * 16 + hi * 8); \
;                 dst = __builtin_amdgcn_mfma_f32_32x32x16_bf16(kf, qf[ks], dst, 0, 0, 0); } } while (0)
; __device__ __forceinline__ void attn_unit(LAS unsigned char* lds, const bf16* PROJ, bf16* DA, const float* sinkl, int unit, int tid, int wid, int lane) {
;     ...
;     const int r32 = lane & 31, hi = lane >> 5;
;     const int hq = hk * 4 + (wid >> 1);
;     const float slope2 = __builtin_amdgcn_exp2f(-(float)(hq + 1)) * LOG2E;
;     const float sink2 = sinkl[hq] * LOG2E;
;     const float NEG = -INFINITY;
;     const bool edge_n = (n == 0) || (n == 31);
; #pragma unroll 1
;     for (int sb = 0; sb < 2; ++sb) {
;         const int a0 = 64 * (wid & 1) + 32 * sb, a = a0 + r32;
;         const size_t qrow = rowb + (size_t)n * 128 + a;
;         bf16x8 qf[4];
; #pragma unroll
;         for (int ks = 0; ks < 4; ++ks) qf[ks] = *(const bf16x8*)(PROJ + qrow * INW + 512 + hq * 64 + ks * 16 + hi * 8);
;         float mrun = sink2, l = 0.f;
;         f32x16 o0, o1;
; #pragma unroll
;         for (int r = 0; r < 16; ++r) { o0[r] = 0.f; o1[r] = 0.f; }
;         const float fb0 = (float)(r32 + 128 - 4 * hi);
;         f32x16 pn;
;     ...
;         ATT_QK(pn, a0);
	v_mul_f32_e32 v204, 0x00000000, v162
	v_mul_f32_e32 v205, 0x3f800000, v162
	v_mul_f32_e32 v206, 0x40000000, v162
	v_mul_f32_e32 v207, 0x40400000, v162
	v_mul_f32_e32 v208, 0x41000000, v162
	v_mul_f32_e32 v209, 0x41100000, v162
	v_mul_f32_e32 v210, 0x41200000, v162
	v_mul_f32_e32 v211, 0x41300000, v162
	v_mul_f32_e32 v212, 0x41800000, v162
	v_mul_f32_e32 v213, 0x41880000, v162
	v_mul_f32_e32 v214, 0x41900000, v162
	v_mul_f32_e32 v215, 0x41980000, v162
	v_mul_f32_e32 v216, 0x41c00000, v162
	v_mul_f32_e32 v217, 0x41c80000, v162
	v_mul_f32_e32 v218, 0x41d00000, v162
	v_mul_f32_e32 v219, 0x41d80000, v162
	v_mul_f32_e32 v220, 0x80000000, v162
	v_mul_f32_e32 v221, 0xbf800000, v162
	v_mul_f32_e32 v222, 0xc0000000, v162
	v_mul_f32_e32 v223, 0xc0400000, v162
	v_mul_f32_e32 v224, 0xc1000000, v162
	v_mul_f32_e32 v225, 0xc1100000, v162
	v_mul_f32_e32 v226, 0xc1200000, v162
	v_mul_f32_e32 v227, 0xc1300000, v162
	v_mul_f32_e32 v228, 0xc1800000, v162
	v_mul_f32_e32 v229, 0xc1880000, v162
	v_mul_f32_e32 v230, 0xc1900000, v162
	v_mul_f32_e32 v231, 0xc1980000, v162
	v_mul_f32_e32 v232, 0xc1c00000, v162
	v_mul_f32_e32 v233, 0xc1c80000, v162
	v_mul_f32_e32 v234, 0xc1d00000, v162
	v_mul_f32_e32 v235, 0xc1d80000, v162
	v_and_b32_e32 v67, 63, v173
	v_bfe_u32 v2, v173, 5, 1
	v_readlane_b32 s24, v238, 7
	v_and_b32_e32 v85, 31, v173
	v_lshlrev_b32_e32 v4, 3, v2
	v_lshlrev_b32_e32 v5, 2, v2
	v_lshlrev_b32_e32 v2, 4, v2
	v_or_b32_e32 v6, 32, v67
	v_readlane_b32 s25, v238, 8
	v_mul_u32_u24_e32 v7, 0x308, v85
	v_mul_u32_u24_e32 v8, 0x308, v6
	v_readlane_b32 s13, v238, 15
	v_add_u32_e32 v84, 0, v2
	v_sub_u32_e32 v95, v85, v5
	v_add3_u32 v96, v8, v4, s13
	v_add3_u32 v97, v7, v4, s13
	v_readlane_b32 s13, v238, 19
	v_add_u32_e32 v99, s80, v6
	s_mov_b32 s36, 0
	v_sub_u32_e32 v98, s13, v5
	s_mov_b64 s[38:39], -1
	s_mov_b32 s23, 0
	v_mul_f32_e32 v94, 0x3fb8aa3b, v191
	v_mov_b32_e32 v3, v66
	v_lshl_add_u64 v[86:87], s[24:25], 0, v[2:3]
	v_readlane_b32 s24, v238, 9
	v_readlane_b32 s25, v238, 10
	s_nop 1
	v_lshl_add_u64 v[88:89], s[24:25], 0, v[2:3]
	s_branch .LBB0_380
